# out-GEMM gated-residual epilogue: residual loads pipelined 8 deep (layers 1-3; layer 0 keeps the f32-input path)
# speedup vs baseline: 1.0094x; 1.0024x over previous
.LBB0_710:
	s_lshl_b64 s[4:5], s[4:5], 2
	v_lshl_or_b32 v166, s9, 8, v176
	s_add_u32 s4, s74, s4
	s_addc_u32 s5, s75, s5
	v_ashrrev_i32_e32 v167, 31, v166
	v_lshl_add_u64 v[50:51], v[166:167], 2, s[4:5]
	s_mov_b64 s[4:5], 0x194e4000
	v_lshl_add_u64 v[54:55], v[50:51], 0, s[4:5]
	s_mov_b32 s4, 0x194e4000
	v_add_co_u32_e32 v50, vcc, s4, v50
	v_lshl_add_u32 v168, s8, 8, v174
	s_nop 0
	v_addc_co_u32_e32 v51, vcc, 0, v51, vcc
	global_load_dwordx4 v[66:69], v[50:51], off
	global_load_dwordx4 v[70:73], v[54:55], off offset:16
	s_nop 0
	global_load_dwordx4 v[50:53], v[54:55], off offset:528
	s_nop 0
	global_load_dwordx4 v[54:57], v[54:55], off offset:512
	v_ashrrev_i32_e32 v169, 31, v168
	v_lshlrev_b64 v[148:149], 11, v[168:169]
	v_lshl_add_u64 v[170:171], v[148:149], 0, v[166:167]
	v_cndmask_b32_e64 v148, 0, 1, s[54:55]
	s_mov_b64 s[4:5], -1
	s_and_b64 vcc, exec, s[62:63]
	v_cmp_ne_u32_e64 s[42:43], 1, v148
	s_cbranch_vccz .Lepi_out_orig
	s_and_b64 s[100:101], exec, s[54:55]
	s_cbranch_scc1 .Lepi_out_orig
	v_lshl_add_u32 v152, v168, 11, v166
	v_lshlrev_b32_e32 v152, 1, v152
	s_mov_b64 s[100:101], s[46:47]
	global_load_dwordx4 v[178:181], v152, s[100:101]
	global_load_dwordx4 v[182:185], v152, s[100:101] offset:256
	s_add_u32 s100, s100, 0x10000
	s_addc_u32 s101, s101, 0
	global_load_dwordx4 v[186:189], v152, s[100:101]
	global_load_dwordx4 v[190:193], v152, s[100:101] offset:256
	s_add_u32 s100, s100, 0x10000
	s_addc_u32 s101, s101, 0
	global_load_dwordx4 v[194:197], v152, s[100:101]
	global_load_dwordx4 v[208:211], v152, s[100:101] offset:256
	s_add_u32 s100, s100, 0x10000
	s_addc_u32 s101, s101, 0
	global_load_dwordx4 v[212:215], v152, s[100:101]
	global_load_dwordx4 v[216:219], v152, s[100:101] offset:256
	s_mov_b64 s[100:101], s[46:47]
	s_add_u32 s4, s46, 0x80000
	s_addc_u32 s5, s47, 0
	s_waitcnt vmcnt(7)
	v_pk_mul_f32 v[144:145], v[144:145], v[66:67]
	v_pk_mul_f32 v[146:147], v[146:147], v[68:69]
	v_pk_mul_f32 v[140:141], v[140:141], v[70:71]
	v_pk_mul_f32 v[142:143], v[142:143], v[72:73]
	v_lshlrev_b32_e32 v148, 16, v178
	v_and_b32_e32 v149, 0xffff0000, v178
	v_lshlrev_b32_e32 v150, 16, v179
	v_and_b32_e32 v151, 0xffff0000, v179
	v_pk_add_f32 v[144:145], v[144:145], v[148:149]
	v_pk_add_f32 v[146:147], v[146:147], v[150:151]
	v_lshlrev_b32_e32 v148, 16, v180
	v_and_b32_e32 v149, 0xffff0000, v180
	v_lshlrev_b32_e32 v150, 16, v181
	v_and_b32_e32 v151, 0xffff0000, v181
	v_pk_add_f32 v[140:141], v[140:141], v[148:149]
	v_pk_add_f32 v[142:143], v[142:143], v[150:151]
	v_cvt_pk_bf16_f32 v178, v144, v145
	v_cvt_pk_bf16_f32 v179, v146, v147
	v_cvt_pk_bf16_f32 v180, v140, v141
	v_cvt_pk_bf16_f32 v181, v142, v143
	global_store_dwordx4 v152, v[178:181], s[100:101]
	s_nop 0
	global_load_dwordx4 v[178:181], v152, s[4:5]
	s_waitcnt vmcnt(8)
	v_pk_mul_f32 v[136:137], v[136:137], v[54:55]
	v_pk_mul_f32 v[138:139], v[138:139], v[56:57]
	v_pk_mul_f32 v[132:133], v[132:133], v[50:51]
	v_pk_mul_f32 v[134:135], v[134:135], v[52:53]
	v_lshlrev_b32_e32 v148, 16, v182
	v_and_b32_e32 v149, 0xffff0000, v182
	v_lshlrev_b32_e32 v150, 16, v183
	v_and_b32_e32 v151, 0xffff0000, v183
	v_pk_add_f32 v[136:137], v[136:137], v[148:149]
	v_pk_add_f32 v[138:139], v[138:139], v[150:151]
	v_lshlrev_b32_e32 v148, 16, v184
	v_and_b32_e32 v149, 0xffff0000, v184
	v_lshlrev_b32_e32 v150, 16, v185
	v_and_b32_e32 v151, 0xffff0000, v185
	v_pk_add_f32 v[132:133], v[132:133], v[148:149]
	v_pk_add_f32 v[134:135], v[134:135], v[150:151]
	v_cvt_pk_bf16_f32 v182, v136, v137
	v_cvt_pk_bf16_f32 v183, v138, v139
	v_cvt_pk_bf16_f32 v184, v132, v133
	v_cvt_pk_bf16_f32 v185, v134, v135
	global_store_dwordx4 v152, v[182:185], s[100:101] offset:256
	s_add_u32 s100, s100, 0x10000
	s_addc_u32 s101, s101, 0
	global_load_dwordx4 v[182:185], v152, s[4:5] offset:256
	s_add_u32 s4, s4, 0x10000
	s_addc_u32 s5, s5, 0
	s_waitcnt vmcnt(9)
	v_pk_mul_f32 v[128:129], v[128:129], v[66:67]
	v_pk_mul_f32 v[130:131], v[130:131], v[68:69]
	v_pk_mul_f32 v[124:125], v[124:125], v[70:71]
	v_pk_mul_f32 v[126:127], v[126:127], v[72:73]
	v_lshlrev_b32_e32 v148, 16, v186
	v_and_b32_e32 v149, 0xffff0000, v186
	v_lshlrev_b32_e32 v150, 16, v187
	v_and_b32_e32 v151, 0xffff0000, v187
	v_pk_add_f32 v[128:129], v[128:129], v[148:149]
	v_pk_add_f32 v[130:131], v[130:131], v[150:151]
	v_lshlrev_b32_e32 v148, 16, v188
	v_and_b32_e32 v149, 0xffff0000, v188
	v_lshlrev_b32_e32 v150, 16, v189
	v_and_b32_e32 v151, 0xffff0000, v189
	v_pk_add_f32 v[124:125], v[124:125], v[148:149]
	v_pk_add_f32 v[126:127], v[126:127], v[150:151]
	v_cvt_pk_bf16_f32 v186, v128, v129
	v_cvt_pk_bf16_f32 v187, v130, v131
	v_cvt_pk_bf16_f32 v188, v124, v125
	v_cvt_pk_bf16_f32 v189, v126, v127
	global_store_dwordx4 v152, v[186:189], s[100:101]
	s_nop 0
	global_load_dwordx4 v[186:189], v152, s[4:5]
	s_waitcnt vmcnt(10)
	v_pk_mul_f32 v[120:121], v[120:121], v[54:55]
	v_pk_mul_f32 v[122:123], v[122:123], v[56:57]
	v_pk_mul_f32 v[116:117], v[116:117], v[50:51]
	v_pk_mul_f32 v[118:119], v[118:119], v[52:53]
	v_lshlrev_b32_e32 v148, 16, v190
	v_and_b32_e32 v149, 0xffff0000, v190
	v_lshlrev_b32_e32 v150, 16, v191
	v_and_b32_e32 v151, 0xffff0000, v191
	v_pk_add_f32 v[120:121], v[120:121], v[148:149]
	v_pk_add_f32 v[122:123], v[122:123], v[150:151]
	v_lshlrev_b32_e32 v148, 16, v192
	v_and_b32_e32 v149, 0xffff0000, v192
	v_lshlrev_b32_e32 v150, 16, v193
	v_and_b32_e32 v151, 0xffff0000, v193
	v_pk_add_f32 v[116:117], v[116:117], v[148:149]
	v_pk_add_f32 v[118:119], v[118:119], v[150:151]
	v_cvt_pk_bf16_f32 v190, v120, v121
	v_cvt_pk_bf16_f32 v191, v122, v123
	v_cvt_pk_bf16_f32 v192, v116, v117
	v_cvt_pk_bf16_f32 v193, v118, v119
	global_store_dwordx4 v152, v[190:193], s[100:101] offset:256
	s_add_u32 s100, s100, 0x10000
	s_addc_u32 s101, s101, 0
	global_load_dwordx4 v[190:193], v152, s[4:5] offset:256
	s_add_u32 s4, s4, 0x10000
	s_addc_u32 s5, s5, 0
	s_waitcnt vmcnt(11)
	v_pk_mul_f32 v[112:113], v[112:113], v[66:67]
	v_pk_mul_f32 v[114:115], v[114:115], v[68:69]
	v_pk_mul_f32 v[108:109], v[108:109], v[70:71]
	v_pk_mul_f32 v[110:111], v[110:111], v[72:73]
	v_lshlrev_b32_e32 v148, 16, v194
	v_and_b32_e32 v149, 0xffff0000, v194
	v_lshlrev_b32_e32 v150, 16, v195
	v_and_b32_e32 v151, 0xffff0000, v195
	v_pk_add_f32 v[112:113], v[112:113], v[148:149]
	v_pk_add_f32 v[114:115], v[114:115], v[150:151]
	v_lshlrev_b32_e32 v148, 16, v196
	v_and_b32_e32 v149, 0xffff0000, v196
	v_lshlrev_b32_e32 v150, 16, v197
	v_and_b32_e32 v151, 0xffff0000, v197
	v_pk_add_f32 v[108:109], v[108:109], v[148:149]
	v_pk_add_f32 v[110:111], v[110:111], v[150:151]
	v_cvt_pk_bf16_f32 v194, v112, v113
	v_cvt_pk_bf16_f32 v195, v114, v115
	v_cvt_pk_bf16_f32 v196, v108, v109
	v_cvt_pk_bf16_f32 v197, v110, v111
	global_store_dwordx4 v152, v[194:197], s[100:101]
	s_nop 0
	global_load_dwordx4 v[194:197], v152, s[4:5]
	s_waitcnt vmcnt(12)
	v_pk_mul_f32 v[104:105], v[104:105], v[54:55]
	v_pk_mul_f32 v[106:107], v[106:107], v[56:57]
	v_pk_mul_f32 v[100:101], v[100:101], v[50:51]
	v_pk_mul_f32 v[102:103], v[102:103], v[52:53]
	v_lshlrev_b32_e32 v148, 16, v208
	v_and_b32_e32 v149, 0xffff0000, v208
	v_lshlrev_b32_e32 v150, 16, v209
	v_and_b32_e32 v151, 0xffff0000, v209
	v_pk_add_f32 v[104:105], v[104:105], v[148:149]
	v_pk_add_f32 v[106:107], v[106:107], v[150:151]
	v_lshlrev_b32_e32 v148, 16, v210
	v_and_b32_e32 v149, 0xffff0000, v210
	v_lshlrev_b32_e32 v150, 16, v211
	v_and_b32_e32 v151, 0xffff0000, v211
	v_pk_add_f32 v[100:101], v[100:101], v[148:149]
	v_pk_add_f32 v[102:103], v[102:103], v[150:151]
	v_cvt_pk_bf16_f32 v208, v104, v105
	v_cvt_pk_bf16_f32 v209, v106, v107
	v_cvt_pk_bf16_f32 v210, v100, v101
	v_cvt_pk_bf16_f32 v211, v102, v103
	global_store_dwordx4 v152, v[208:211], s[100:101] offset:256
	s_add_u32 s100, s100, 0x10000
	s_addc_u32 s101, s101, 0
	global_load_dwordx4 v[208:211], v152, s[4:5] offset:256
	s_add_u32 s4, s4, 0x10000
	s_addc_u32 s5, s5, 0
	s_waitcnt vmcnt(13)
	v_pk_mul_f32 v[94:95], v[94:95], v[66:67]
	v_pk_mul_f32 v[96:97], v[96:97], v[68:69]
	v_pk_mul_f32 v[90:91], v[90:91], v[70:71]
	v_pk_mul_f32 v[92:93], v[92:93], v[72:73]
	v_lshlrev_b32_e32 v148, 16, v212
	v_and_b32_e32 v149, 0xffff0000, v212
	v_lshlrev_b32_e32 v150, 16, v213
	v_and_b32_e32 v151, 0xffff0000, v213
	v_pk_add_f32 v[94:95], v[94:95], v[148:149]
	v_pk_add_f32 v[96:97], v[96:97], v[150:151]
	v_lshlrev_b32_e32 v148, 16, v214
	v_and_b32_e32 v149, 0xffff0000, v214
	v_lshlrev_b32_e32 v150, 16, v215
	v_and_b32_e32 v151, 0xffff0000, v215
	v_pk_add_f32 v[90:91], v[90:91], v[148:149]
	v_pk_add_f32 v[92:93], v[92:93], v[150:151]
	v_cvt_pk_bf16_f32 v212, v94, v95
	v_cvt_pk_bf16_f32 v213, v96, v97
	v_cvt_pk_bf16_f32 v214, v90, v91
	v_cvt_pk_bf16_f32 v215, v92, v93
	global_store_dwordx4 v152, v[212:215], s[100:101]
	s_nop 0
	global_load_dwordx4 v[212:215], v152, s[4:5]
	s_waitcnt vmcnt(14)
	v_pk_mul_f32 v[86:87], v[86:87], v[54:55]
	v_pk_mul_f32 v[88:89], v[88:89], v[56:57]
	v_pk_mul_f32 v[82:83], v[82:83], v[50:51]
	v_pk_mul_f32 v[84:85], v[84:85], v[52:53]
	v_lshlrev_b32_e32 v148, 16, v216
	v_and_b32_e32 v149, 0xffff0000, v216
	v_lshlrev_b32_e32 v150, 16, v217
	v_and_b32_e32 v151, 0xffff0000, v217
	v_pk_add_f32 v[86:87], v[86:87], v[148:149]
	v_pk_add_f32 v[88:89], v[88:89], v[150:151]
	v_lshlrev_b32_e32 v148, 16, v218
	v_and_b32_e32 v149, 0xffff0000, v218
	v_lshlrev_b32_e32 v150, 16, v219
	v_and_b32_e32 v151, 0xffff0000, v219
	v_pk_add_f32 v[82:83], v[82:83], v[148:149]
	v_pk_add_f32 v[84:85], v[84:85], v[150:151]
	v_cvt_pk_bf16_f32 v216, v86, v87
	v_cvt_pk_bf16_f32 v217, v88, v89
	v_cvt_pk_bf16_f32 v218, v82, v83
	v_cvt_pk_bf16_f32 v219, v84, v85
	global_store_dwordx4 v152, v[216:219], s[100:101] offset:256
	s_add_u32 s100, s100, 0x10000
	s_addc_u32 s101, s101, 0
	global_load_dwordx4 v[216:219], v152, s[4:5] offset:256
	s_add_u32 s4, s46, 0x80000
	s_addc_u32 s5, s47, 0
	s_waitcnt vmcnt(14)
	v_pk_mul_f32 v[78:79], v[78:79], v[66:67]
	v_pk_mul_f32 v[80:81], v[80:81], v[68:69]
	v_pk_mul_f32 v[74:75], v[74:75], v[70:71]
	v_pk_mul_f32 v[76:77], v[76:77], v[72:73]
	v_lshlrev_b32_e32 v148, 16, v178
	v_and_b32_e32 v149, 0xffff0000, v178
	v_lshlrev_b32_e32 v150, 16, v179
	v_and_b32_e32 v151, 0xffff0000, v179
	v_pk_add_f32 v[78:79], v[78:79], v[148:149]
	v_pk_add_f32 v[80:81], v[80:81], v[150:151]
	v_lshlrev_b32_e32 v148, 16, v180
	v_and_b32_e32 v149, 0xffff0000, v180
	v_lshlrev_b32_e32 v150, 16, v181
	v_and_b32_e32 v151, 0xffff0000, v181
	v_pk_add_f32 v[74:75], v[74:75], v[148:149]
	v_pk_add_f32 v[76:77], v[76:77], v[150:151]
	v_cvt_pk_bf16_f32 v178, v78, v79
	v_cvt_pk_bf16_f32 v179, v80, v81
	v_cvt_pk_bf16_f32 v180, v74, v75
	v_cvt_pk_bf16_f32 v181, v76, v77
	global_store_dwordx4 v152, v[178:181], s[4:5]
	s_waitcnt vmcnt(13)
	v_pk_mul_f32 v[62:63], v[62:63], v[54:55]
	v_pk_mul_f32 v[64:65], v[64:65], v[56:57]
	v_pk_mul_f32 v[58:59], v[58:59], v[50:51]
	v_pk_mul_f32 v[60:61], v[60:61], v[52:53]
	v_lshlrev_b32_e32 v148, 16, v182
	v_and_b32_e32 v149, 0xffff0000, v182
	v_lshlrev_b32_e32 v150, 16, v183
	v_and_b32_e32 v151, 0xffff0000, v183
	v_pk_add_f32 v[62:63], v[62:63], v[148:149]
	v_pk_add_f32 v[64:65], v[64:65], v[150:151]
	v_lshlrev_b32_e32 v148, 16, v184
	v_and_b32_e32 v149, 0xffff0000, v184
	v_lshlrev_b32_e32 v150, 16, v185
	v_and_b32_e32 v151, 0xffff0000, v185
	v_pk_add_f32 v[58:59], v[58:59], v[148:149]
	v_pk_add_f32 v[60:61], v[60:61], v[150:151]
	v_cvt_pk_bf16_f32 v182, v62, v63
	v_cvt_pk_bf16_f32 v183, v64, v65
	v_cvt_pk_bf16_f32 v184, v58, v59
	v_cvt_pk_bf16_f32 v185, v60, v61
	global_store_dwordx4 v152, v[182:185], s[4:5] offset:256
	s_add_u32 s4, s4, 0x10000
	s_addc_u32 s5, s5, 0
	s_waitcnt vmcnt(12)
	v_pk_mul_f32 v[46:47], v[46:47], v[66:67]
	v_pk_mul_f32 v[48:49], v[48:49], v[68:69]
	v_pk_mul_f32 v[42:43], v[42:43], v[70:71]
	v_pk_mul_f32 v[44:45], v[44:45], v[72:73]
	v_lshlrev_b32_e32 v148, 16, v186
	v_and_b32_e32 v149, 0xffff0000, v186
	v_lshlrev_b32_e32 v150, 16, v187
	v_and_b32_e32 v151, 0xffff0000, v187
	v_pk_add_f32 v[46:47], v[46:47], v[148:149]
	v_pk_add_f32 v[48:49], v[48:49], v[150:151]
	v_lshlrev_b32_e32 v148, 16, v188
	v_and_b32_e32 v149, 0xffff0000, v188
	v_lshlrev_b32_e32 v150, 16, v189
	v_and_b32_e32 v151, 0xffff0000, v189
	v_pk_add_f32 v[42:43], v[42:43], v[148:149]
	v_pk_add_f32 v[44:45], v[44:45], v[150:151]
	v_cvt_pk_bf16_f32 v186, v46, v47
	v_cvt_pk_bf16_f32 v187, v48, v49
	v_cvt_pk_bf16_f32 v188, v42, v43
	v_cvt_pk_bf16_f32 v189, v44, v45
	global_store_dwordx4 v152, v[186:189], s[4:5]
	s_waitcnt vmcnt(11)
	v_pk_mul_f32 v[38:39], v[38:39], v[54:55]
	v_pk_mul_f32 v[40:41], v[40:41], v[56:57]
	v_pk_mul_f32 v[34:35], v[34:35], v[50:51]
	v_pk_mul_f32 v[36:37], v[36:37], v[52:53]
	v_lshlrev_b32_e32 v148, 16, v190
	v_and_b32_e32 v149, 0xffff0000, v190
	v_lshlrev_b32_e32 v150, 16, v191
	v_and_b32_e32 v151, 0xffff0000, v191
	v_pk_add_f32 v[38:39], v[38:39], v[148:149]
	v_pk_add_f32 v[40:41], v[40:41], v[150:151]
	v_lshlrev_b32_e32 v148, 16, v192
	v_and_b32_e32 v149, 0xffff0000, v192
	v_lshlrev_b32_e32 v150, 16, v193
	v_and_b32_e32 v151, 0xffff0000, v193
	v_pk_add_f32 v[34:35], v[34:35], v[148:149]
	v_pk_add_f32 v[36:37], v[36:37], v[150:151]
	v_cvt_pk_bf16_f32 v190, v38, v39
	v_cvt_pk_bf16_f32 v191, v40, v41
	v_cvt_pk_bf16_f32 v192, v34, v35
	v_cvt_pk_bf16_f32 v193, v36, v37
	global_store_dwordx4 v152, v[190:193], s[4:5] offset:256
	s_add_u32 s4, s4, 0x10000
	s_addc_u32 s5, s5, 0
	s_waitcnt vmcnt(10)
	v_pk_mul_f32 v[30:31], v[30:31], v[66:67]
	v_pk_mul_f32 v[32:33], v[32:33], v[68:69]
	v_pk_mul_f32 v[26:27], v[26:27], v[70:71]
	v_pk_mul_f32 v[28:29], v[28:29], v[72:73]
	v_lshlrev_b32_e32 v148, 16, v194
	v_and_b32_e32 v149, 0xffff0000, v194
	v_lshlrev_b32_e32 v150, 16, v195
	v_and_b32_e32 v151, 0xffff0000, v195
	v_pk_add_f32 v[30:31], v[30:31], v[148:149]
	v_pk_add_f32 v[32:33], v[32:33], v[150:151]
	v_lshlrev_b32_e32 v148, 16, v196
	v_and_b32_e32 v149, 0xffff0000, v196
	v_lshlrev_b32_e32 v150, 16, v197
	v_and_b32_e32 v151, 0xffff0000, v197
	v_pk_add_f32 v[26:27], v[26:27], v[148:149]
	v_pk_add_f32 v[28:29], v[28:29], v[150:151]
	v_cvt_pk_bf16_f32 v194, v30, v31
	v_cvt_pk_bf16_f32 v195, v32, v33
	v_cvt_pk_bf16_f32 v196, v26, v27
	v_cvt_pk_bf16_f32 v197, v28, v29
	global_store_dwordx4 v152, v[194:197], s[4:5]
	s_waitcnt vmcnt(9)
	v_pk_mul_f32 v[22:23], v[22:23], v[54:55]
	v_pk_mul_f32 v[24:25], v[24:25], v[56:57]
	v_pk_mul_f32 v[18:19], v[18:19], v[50:51]
	v_pk_mul_f32 v[20:21], v[20:21], v[52:53]
	v_lshlrev_b32_e32 v148, 16, v208
	v_and_b32_e32 v149, 0xffff0000, v208
	v_lshlrev_b32_e32 v150, 16, v209
	v_and_b32_e32 v151, 0xffff0000, v209
	v_pk_add_f32 v[22:23], v[22:23], v[148:149]
	v_pk_add_f32 v[24:25], v[24:25], v[150:151]
	v_lshlrev_b32_e32 v148, 16, v210
	v_and_b32_e32 v149, 0xffff0000, v210
	v_lshlrev_b32_e32 v150, 16, v211
	v_and_b32_e32 v151, 0xffff0000, v211
	v_pk_add_f32 v[18:19], v[18:19], v[148:149]
	v_pk_add_f32 v[20:21], v[20:21], v[150:151]
	v_cvt_pk_bf16_f32 v208, v22, v23
	v_cvt_pk_bf16_f32 v209, v24, v25
	v_cvt_pk_bf16_f32 v210, v18, v19
	v_cvt_pk_bf16_f32 v211, v20, v21
	global_store_dwordx4 v152, v[208:211], s[4:5] offset:256
	s_add_u32 s4, s4, 0x10000
	s_addc_u32 s5, s5, 0
	s_waitcnt vmcnt(8)
	v_pk_mul_f32 v[14:15], v[14:15], v[66:67]
	v_pk_mul_f32 v[16:17], v[16:17], v[68:69]
	v_pk_mul_f32 v[10:11], v[10:11], v[70:71]
	v_pk_mul_f32 v[12:13], v[12:13], v[72:73]
	v_lshlrev_b32_e32 v148, 16, v212
	v_and_b32_e32 v149, 0xffff0000, v212
	v_lshlrev_b32_e32 v150, 16, v213
	v_and_b32_e32 v151, 0xffff0000, v213
	v_pk_add_f32 v[14:15], v[14:15], v[148:149]
	v_pk_add_f32 v[16:17], v[16:17], v[150:151]
	v_lshlrev_b32_e32 v148, 16, v214
	v_and_b32_e32 v149, 0xffff0000, v214
	v_lshlrev_b32_e32 v150, 16, v215
	v_and_b32_e32 v151, 0xffff0000, v215
	v_pk_add_f32 v[10:11], v[10:11], v[148:149]
	v_pk_add_f32 v[12:13], v[12:13], v[150:151]
	v_cvt_pk_bf16_f32 v212, v14, v15
	v_cvt_pk_bf16_f32 v213, v16, v17
	v_cvt_pk_bf16_f32 v214, v10, v11
	v_cvt_pk_bf16_f32 v215, v12, v13
	global_store_dwordx4 v152, v[212:215], s[4:5]
	s_waitcnt vmcnt(7)
	v_pk_mul_f32 v[6:7], v[6:7], v[54:55]
	v_pk_mul_f32 v[8:9], v[8:9], v[56:57]
	v_pk_mul_f32 v[2:3], v[2:3], v[50:51]
	v_pk_mul_f32 v[4:5], v[4:5], v[52:53]
	v_lshlrev_b32_e32 v148, 16, v216
	v_and_b32_e32 v149, 0xffff0000, v216
	v_lshlrev_b32_e32 v150, 16, v217
	v_and_b32_e32 v151, 0xffff0000, v217
	v_pk_add_f32 v[6:7], v[6:7], v[148:149]
	v_pk_add_f32 v[8:9], v[8:9], v[150:151]
	v_lshlrev_b32_e32 v148, 16, v218
	v_and_b32_e32 v149, 0xffff0000, v218
	v_lshlrev_b32_e32 v150, 16, v219
	v_and_b32_e32 v151, 0xffff0000, v219
	v_pk_add_f32 v[2:3], v[2:3], v[148:149]
	v_pk_add_f32 v[4:5], v[4:5], v[150:151]
	v_cvt_pk_bf16_f32 v216, v6, v7
	v_cvt_pk_bf16_f32 v217, v8, v9
	v_cvt_pk_bf16_f32 v218, v2, v3
	v_cvt_pk_bf16_f32 v219, v4, v5
	global_store_dwordx4 v152, v[216:219], s[4:5] offset:256
	s_branch .LBB0_820
.Lepi_out_orig:
	s_waitcnt vmcnt(0)
	v_pk_mul_f32 v[146:147], v[146:147], v[68:69]
	v_pk_mul_f32 v[144:145], v[144:145], v[66:67]
	v_pk_mul_f32 v[142:143], v[142:143], v[72:73]
	v_pk_mul_f32 v[140:141], v[140:141], v[70:71]
	s_cbranch_vccz .LBB0_715
	s_and_b64 vcc, exec, s[42:43]
	s_cbranch_vccnz .LBB0_825
	v_lshl_add_u64 v[148:149], v[170:171], 2, s[38:39]
	global_load_dwordx4 v[152:155], v[148:149], off offset:16
	s_nop 0
	global_load_dwordx4 v[148:151], v[148:149], off
	v_lshl_add_u64 v[172:173], v[170:171], 1, s[46:47]
	s_cbranch_execnz .LBB0_714
